# scan: write-through o stores and progress word with counted waits; type-0 compute wave no longer drains its own stores each step
# speedup vs baseline: 1.0012x; 1.0012x over previous
.LBB0_21:
	s_lshr_b32 s95, s85, 6
	s_cmp_gt_u32 s2, 63
	s_cbranch_scc1 .Lpf_noinit
	s_cmp_lg_u32 s85, 0
	s_cbranch_scc1 .Lpf_noinit
	s_add_u32 s98, s54, 0x1ec04000
	s_addc_u32 s99, s55, 0
	s_lshl_b32 s100, s2, 8
	s_add_u32 s98, s98, s100
	s_addc_u32 s99, s99, 0
	v_mov_b32_e32 v239, 0
	global_store_dword v239, v239, s[98:99] sc0 sc1
	v_mov_b32_e32 v238, -1
	global_store_dword v239, v238, s[98:99] offset:16 sc0 sc1
	global_store_dword v239, v238, s[98:99] offset:20 sc0 sc1
	global_store_dword v239, v238, s[98:99] offset:24 sc0 sc1
	global_store_dword v239, v238, s[98:99] offset:28 sc0 sc1

.LBB0_497:
	s_andn2_b64 vcc, exec, s[0:1]
	s_cbranch_vccnz .LBB0_520
	s_and_b32 s3, s2, 1
	s_ashr_i32 s14, s2, 1
	s_bitcmp1_b32 s2, 0
	s_cselect_b64 s[0:1], -1, 0
	s_add_u32 s12, s54, 0x15c00000
	s_addc_u32 s13, s55, 0
	s_cmp_eq_u32 s3, 0
	s_cselect_b64 s[6:7], -1, 0
	s_mov_b32 s3, 0x380000
	s_and_b64 s[8:9], s[6:7], exec
	s_cselect_b32 s3, s3, 0x480000
	s_cselect_b32 s9, s52, s12
	s_mul_hi_i32 s12, s3, s14
	s_mul_i32 s3, s3, s14
	s_cselect_b32 s8, s53, s13
	s_add_u32 s16, s9, s3
	v_mbcnt_lo_u32_b32 v0, -1, 0
	s_addc_u32 s17, s8, s12
	v_mbcnt_hi_u32_b32 v190, -1, v0
	v_cndmask_b32_e64 v0, 0, 1, s[0:1]
	s_cmpk_lt_u32 s85, 0x100
	s_mov_b64 s[8:9], -1
	v_cmp_ne_u32_e64 s[0:1], 1, v0
	s_cbranch_scc0 .LBB0_507
	s_ashr_i32 s3, s2, 3
	s_and_b32 s13, s14, 3
	s_setprio 3
	s_add_u32 s98, s54, 0x1ec04010
	s_addc_u32 s99, s55, 0
	s_lshl_b32 s100, s2, 8
	s_add_u32 s98, s98, s100
	s_addc_u32 s99, s99, 0
	s_lshl_b32 s100, s95, 2
	s_add_u32 s98, s98, s100
	s_addc_u32 s99, s99, 0
	v_mov_b32_e32 v241, 0
	s_and_b64 vcc, exec, s[0:1]
	s_mul_i32 s12, s95, 0x1400
	s_cbranch_vccnz .LBB0_503
	s_lshl_b32 s8, s14, 6
	s_ashr_i32 s9, s8, 31
	s_lshl_b64 s[8:9], s[8:9], 2
	v_mov_b32_e32 v20, v190
	s_add_u32 s8, s54, s8
	s_addc_u32 s9, s55, s9
	v_ashrrev_i32_e32 v22, 5, v20
	s_lshl_b32 s14, s95, 12
	v_ashrrev_i32_e32 v21, 31, v20
	v_lshlrev_b32_e32 v16, 7, v22
	s_add_u32 s14, s16, s14
	v_lshl_add_u64 v[0:1], v[20:21], 2, s[8:9]
	v_and_b32_e32 v21, 31, v20
	v_ashrrev_i32_e32 v17, 31, v16
	s_addc_u32 s15, s17, 0
	v_add_co_u32_e32 v0, vcc, 0x1a40000, v0
	v_mov_b32_e32 v165, 0
	v_lshlrev_b32_e32 v164, 3, v21
	v_lshl_add_u64 v[16:17], v[16:17], 1, s[14:15]
	v_addc_co_u32_e32 v1, vcc, 0, v1, vcc
	v_lshl_add_u64 v[172:173], v[16:17], 0, v[164:165]
	global_load_dword v19, v[0:1], off
	global_load_dwordx2 v[188:189], v[172:173], off
	global_load_dwordx2 v[182:183], v[172:173], off offset:512
	global_load_dwordx2 v[178:179], v[172:173], off offset:1024
	global_load_dwordx2 v[174:175], v[172:173], off offset:1536
	global_load_dwordx2 v[186:187], v[172:173], off offset:2048
	global_load_dwordx2 v[184:185], v[172:173], off offset:2560
	global_load_dwordx2 v[180:181], v[172:173], off offset:3072
	global_load_dwordx2 v[176:177], v[172:173], off offset:3584
	s_movk_i32 s8, 0x140
	v_bfe_u32 v23, v20, 2, 3
	s_movk_i32 s26, 0x50
	v_lshlrev_b32_e32 v20, 4, v20
	v_lshlrev_b32_e32 v193, 4, v22
	v_mul_lo_u32 v24, v22, s8
	v_lshl_or_b32 v22, v22, 3, v23
	s_lshl_b32 s8, s13, 8
	s_add_i32 s14, s12, 0
	s_lshl_b32 s15, s3, 23
	v_mul_u32_u24_e32 v192, 0x110, v21
	v_mul_u32_u24_e32 v194, 0x90, v21
	v_lshlrev_b32_e32 v21, 1, v21
	v_and_b32_e32 v20, 48, v20
	v_mul_lo_u32 v23, v22, s26
	s_and_b32 s26, s85, 0xc0
	s_add_i32 s14, s14, 0x1e800
	s_or_b32 s8, s15, s8
	s_waitcnt lgkmcnt(0)
	s_barrier
	v_add3_u32 v195, s14, v24, v21
	v_lshl_or_b32 v164, v22, 11, v20
	v_add_u32_e32 v21, s14, v23
	s_or_b32 s8, s8, s26
	s_mov_b32 s9, 0
	v_mov_b32_e32 v191, 0x12000
	v_mov_b32_e32 v167, v165
	v_mov_b32_e32 v169, v165
	v_mov_b32_e32 v171, v165
	v_mov_b32_e32 v0, v165
	v_mov_b32_e32 v1, v165
	v_mov_b32_e32 v2, v165
	v_mov_b32_e32 v3, v165
	v_mov_b32_e32 v4, v165
	v_mov_b32_e32 v5, v165
	v_mov_b32_e32 v6, v165
	v_mov_b32_e32 v7, v165
	v_mov_b32_e32 v8, v165
	v_mov_b32_e32 v9, v165
	v_mov_b32_e32 v10, v165
	v_mov_b32_e32 v11, v165
	v_mov_b32_e32 v12, v165
	v_mov_b32_e32 v13, v165
	v_mov_b32_e32 v14, v165
	v_mov_b32_e32 v15, v165
	v_mov_b32_e32 v16, v165
	v_mov_b32_e32 v17, v165
	v_mov_b32_e32 v18, v165
	v_add_u32_e32 v166, 0x8000, v164
	v_add_u32_e32 v168, 0x10000, v164
	v_add_u32_e32 v170, 0x18000, v164
	s_bitset1_b32 s8, 10
	v_add_u32_e32 v196, v21, v20
	v_mov_b32_e32 v20, v165
	v_mov_b32_e32 v21, v165
	v_mov_b32_e32 v22, v165
	v_mov_b32_e32 v23, v165
	v_mov_b32_e32 v24, v165
	v_mov_b32_e32 v25, v165
	v_mov_b32_e32 v26, v165
	v_mov_b32_e32 v27, v165
	v_mov_b32_e32 v28, v165
	v_mov_b32_e32 v29, v165
	v_mov_b32_e32 v30, v165
	v_mov_b32_e32 v31, v165
	v_mov_b32_e32 v32, v165
	v_mov_b32_e32 v33, v165
	v_mov_b32_e32 v34, v165
	v_mov_b32_e32 v35, v165
	v_mov_b32_e32 v36, v165
	v_mov_b32_e32 v37, v165
	v_mov_b32_e32 v38, v165
	v_mov_b32_e32 v39, v165
	v_mov_b32_e32 v40, v165
	v_mov_b32_e32 v41, v165
	v_mov_b32_e32 v42, v165
	v_mov_b32_e32 v43, v165
	s_waitcnt vmcnt(0)
	v_mul_f32_e32 v19, 0x3fb8aa3b, v19
	v_exp_f32_e32 v197, v19
	v_mov_b32_e32 v19, v165
	v_mov_b32_e32 v44, v165
	v_mov_b32_e32 v45, v165
	v_mov_b32_e32 v46, v165
	v_mov_b32_e32 v47, v165
	v_mov_b32_e32 v48, v165
	v_mov_b32_e32 v49, v165
	v_mov_b32_e32 v50, v165
	v_mov_b32_e32 v51, v165
	v_mov_b32_e32 v52, v165
	v_mov_b32_e32 v53, v165
	v_mov_b32_e32 v54, v165
	v_mov_b32_e32 v55, v165
	v_mov_b32_e32 v56, v165
	v_mov_b32_e32 v57, v165
	v_mov_b32_e32 v58, v165
	v_mov_b32_e32 v59, v165
	v_mov_b32_e32 v60, v165
	v_mov_b32_e32 v61, v165
	v_mov_b32_e32 v62, v165
	v_mov_b32_e32 v63, v165
.LBB0_501:
	s_bitcmp1_b32 s9, 0
	s_cselect_b32 s14, 0xf400, 0
	s_add_i32 s14, s14, 0
	v_add3_u32 v152, s14, v192, v193
	ds_read_b128 v[64:67], v152
	ds_read_b128 v[88:91], v152 offset:32
	ds_read_b128 v[68:71], v152 offset:8704
	ds_read_b128 v[92:95], v152 offset:8736
	ds_read_b128 v[72:75], v152 offset:17408
	ds_read_b128 v[128:131], v152 offset:17440
	ds_read_b128 v[80:83], v152 offset:26112
	ds_read_b128 v[136:139], v152 offset:26144
	v_add3_u32 v198, s14, v194, v193
	v_cvt_pk_bf16_f32 v84, v0, v1
	v_cvt_pk_bf16_f32 v85, v2, v3
	v_cvt_pk_bf16_f32 v86, v4, v5
	v_cvt_pk_bf16_f32 v87, v6, v7
	s_waitcnt lgkmcnt(7)
	s_nop 0
	v_mfma_f32_32x32x16_bf16 v[112:127], v[64:67], v[84:87], 0
	s_waitcnt lgkmcnt(5)
	v_mfma_f32_32x32x16_bf16 v[96:111], v[68:71], v[84:87], 0
	s_waitcnt lgkmcnt(3)
	v_mfma_f32_32x32x16_bf16 v[64:79], v[72:75], v[84:87], 0
	ds_read_b128 v[132:135], v152 offset:64
	ds_read_b128 v[140:143], v152 offset:8768
	ds_read_b128 v[148:151], v152 offset:17472
	ds_read_b128 v[144:147], v152 offset:26176
	v_cvt_pk_bf16_f32 v160, v8, v9
	v_cvt_pk_bf16_f32 v161, v10, v11
	v_cvt_pk_bf16_f32 v162, v12, v13
	v_cvt_pk_bf16_f32 v163, v14, v15
	s_nop 1
	v_mfma_f32_32x32x16_bf16 v[112:127], v[88:91], v[160:163], v[112:127]
	v_mfma_f32_32x32x16_bf16 v[96:111], v[92:95], v[160:163], v[96:111]
	s_waitcnt lgkmcnt(6)
	v_mfma_f32_32x32x16_bf16 v[64:79], v[128:131], v[160:163], v[64:79]
	ds_read_b128 v[88:91], v152 offset:96
	ds_read_b128 v[92:95], v152 offset:8800
	ds_read_b128 v[128:131], v152 offset:17504
	ds_read_b128 v[156:159], v152 offset:26208
	v_cvt_pk_bf16_f32 v200, v16, v17
	v_cvt_pk_bf16_f32 v201, v18, v19
	v_cvt_pk_bf16_f32 v202, v20, v21
	v_cvt_pk_bf16_f32 v203, v22, v23
	s_waitcnt lgkmcnt(7)
	s_nop 0
	v_mfma_f32_32x32x16_bf16 v[112:127], v[132:135], v[200:203], v[112:127]
	s_waitcnt lgkmcnt(6)
	v_mfma_f32_32x32x16_bf16 v[96:111], v[140:143], v[200:203], v[96:111]
	s_waitcnt lgkmcnt(5)
	v_mfma_f32_32x32x16_bf16 v[64:79], v[148:151], v[200:203], v[64:79]
	ds_read_b128 v[132:135], v152 offset:128
	ds_read_b128 v[140:143], v152 offset:8832
	ds_read_b128 v[148:151], v152 offset:17536
	ds_read_b128 v[204:207], v152 offset:26240
	v_cvt_pk_bf16_f32 v208, v24, v25
	v_cvt_pk_bf16_f32 v209, v26, v27
	v_cvt_pk_bf16_f32 v210, v28, v29
	v_cvt_pk_bf16_f32 v211, v30, v31
	s_waitcnt lgkmcnt(7)
	s_nop 0
	v_mfma_f32_32x32x16_bf16 v[112:127], v[88:91], v[208:211], v[112:127]
	s_waitcnt lgkmcnt(6)
	v_mfma_f32_32x32x16_bf16 v[96:111], v[92:95], v[208:211], v[96:111]
	s_waitcnt lgkmcnt(5)
	v_mfma_f32_32x32x16_bf16 v[64:79], v[128:131], v[208:211], v[64:79]
	ds_read_b128 v[88:91], v152 offset:160
	ds_read_b128 v[92:95], v152 offset:8864
	ds_read_b128 v[128:131], v152 offset:17568
	ds_read_b128 v[212:215], v152 offset:26272
	v_cvt_pk_bf16_f32 v216, v32, v33
	v_cvt_pk_bf16_f32 v217, v34, v35
	v_cvt_pk_bf16_f32 v218, v36, v37
	v_cvt_pk_bf16_f32 v219, v38, v39
	s_waitcnt lgkmcnt(7)
	s_nop 0
	v_mfma_f32_32x32x16_bf16 v[112:127], v[132:135], v[216:219], v[112:127]
	s_waitcnt lgkmcnt(6)
	v_mfma_f32_32x32x16_bf16 v[96:111], v[140:143], v[216:219], v[96:111]
	s_waitcnt lgkmcnt(5)
	v_mfma_f32_32x32x16_bf16 v[64:79], v[148:151], v[216:219], v[64:79]
	ds_read_b128 v[132:135], v152 offset:192
	ds_read_b128 v[140:143], v152 offset:8896
	ds_read_b128 v[148:151], v152 offset:17600
	ds_read_b128 v[220:223], v152 offset:26304
	v_cvt_pk_bf16_f32 v224, v40, v41
	v_cvt_pk_bf16_f32 v225, v42, v43
	v_cvt_pk_bf16_f32 v226, v44, v45
	v_cvt_pk_bf16_f32 v227, v46, v47
	s_waitcnt lgkmcnt(7)
	s_nop 0
	v_mfma_f32_32x32x16_bf16 v[112:127], v[88:91], v[224:227], v[112:127]
	s_waitcnt lgkmcnt(6)
	v_mfma_f32_32x32x16_bf16 v[96:111], v[92:95], v[224:227], v[96:111]
	s_waitcnt lgkmcnt(5)
	v_mfma_f32_32x32x16_bf16 v[64:79], v[128:131], v[224:227], v[64:79]
	ds_read_b128 v[88:91], v152 offset:224
	ds_read_b128 v[92:95], v152 offset:8928
	ds_read_b128 v[228:231], v152 offset:17632
	ds_read_b128 v[152:155], v152 offset:26336
	v_cvt_pk_bf16_f32 v232, v48, v49
	v_cvt_pk_bf16_f32 v233, v50, v51
	v_cvt_pk_bf16_f32 v234, v52, v53
	v_cvt_pk_bf16_f32 v235, v54, v55
	s_waitcnt lgkmcnt(7)
	s_nop 0
	v_mfma_f32_32x32x16_bf16 v[112:127], v[132:135], v[232:235], v[112:127]
	s_waitcnt lgkmcnt(6)
	v_mfma_f32_32x32x16_bf16 v[96:111], v[140:143], v[232:235], v[96:111]
	s_waitcnt lgkmcnt(5)
	v_mfma_f32_32x32x16_bf16 v[64:79], v[148:151], v[232:235], v[64:79]
	ds_read_b128 v[148:151], v198 offset:53248
	ds_read_b128 v[132:135], v198 offset:53280
	ds_read_b128 v[140:143], v198 offset:57856
	ds_read_b128 v[128:131], v198 offset:57888
	v_cvt_pk_bf16_f32 v236, v56, v57
	v_cvt_pk_bf16_f32 v237, v58, v59
	v_cvt_pk_bf16_f32 v238, v60, v61
	v_cvt_pk_bf16_f32 v239, v62, v63
	s_waitcnt lgkmcnt(7)
	s_nop 0
	v_mfma_f32_32x32x16_bf16 v[112:127], v[88:91], v[236:239], v[112:127]
	s_waitcnt lgkmcnt(6)
	v_mfma_f32_32x32x16_bf16 v[96:111], v[92:95], v[236:239], v[96:111]
	s_waitcnt lgkmcnt(5)
	v_mfma_f32_32x32x16_bf16 v[64:79], v[228:231], v[236:239], v[64:79]
	s_waitcnt vmcnt(11)
	v_lshlrev_b32_e32 v88, 16, v188
	v_and_b32_e32 v89, 0xffff0000, v188
	s_nop 4
	v_add_f32_e64 v112, v88, -v112
	v_add_f32_e64 v113, v89, -v113
	v_lshlrev_b32_e32 v88, 16, v189
	v_and_b32_e32 v89, 0xffff0000, v189
	v_pk_add_f32 v[114:115], v[88:89], v[114:115] neg_lo:[0,1] neg_hi:[0,1]
	v_mfma_f32_32x32x16_bf16 v[80:95], v[80:83], v[84:87], 0
	s_waitcnt vmcnt(7)
	v_lshlrev_b32_e32 v188, 16, v186
	v_and_b32_e32 v189, 0xffff0000, v186
	v_lshlrev_b32_e32 v186, 16, v187
	v_and_b32_e32 v187, 0xffff0000, v187
	v_pk_add_f32 v[98:99], v[186:187], v[98:99] neg_lo:[0,1] neg_hi:[0,1]
	v_lshlrev_b32_e32 v186, 16, v182
	v_and_b32_e32 v187, 0xffff0000, v182
	v_mfma_f32_32x32x16_bf16 v[80:95], v[136:139], v[160:163], v[80:95]
	v_lshlrev_b32_e32 v136, 16, v183
	v_and_b32_e32 v137, 0xffff0000, v183
	v_add_f32_e64 v118, v136, -v118
	v_add_f32_e64 v119, v137, -v119
	s_waitcnt vmcnt(6)
	v_lshlrev_b32_e32 v136, 16, v184
	v_and_b32_e32 v137, 0xffff0000, v184
	v_pk_add_f32 v[136:137], v[136:137], v[100:101] neg_lo:[0,1] neg_hi:[0,1]
	v_lshlrev_b32_e32 v100, 16, v185
	v_mfma_f32_32x32x16_bf16 v[80:95], v[144:147], v[200:203], v[80:95]
	v_and_b32_e32 v101, 0xffff0000, v185
	v_add_f32_e64 v138, v100, -v102
	v_add_f32_e64 v139, v101, -v103
	v_lshlrev_b32_e32 v100, 16, v178
	v_and_b32_e32 v101, 0xffff0000, v178
	v_pk_add_f32 v[100:101], v[100:101], v[120:121] neg_lo:[0,1] neg_hi:[0,1]
	s_waitcnt vmcnt(5)
	v_lshlrev_b32_e32 v120, 16, v180
	v_and_b32_e32 v121, 0xffff0000, v180
	v_mfma_f32_32x32x16_bf16 v[80:95], v[156:159], v[208:211], v[80:95]
	v_lshlrev_b32_e32 v102, 16, v179
	v_and_b32_e32 v103, 0xffff0000, v179
	v_add_f32_e64 v120, v120, -v104
	v_add_f32_e64 v121, v121, -v105
	v_lshlrev_b32_e32 v104, 16, v181
	v_and_b32_e32 v105, 0xffff0000, v181
	v_pk_add_f32 v[102:103], v[102:103], v[122:123] neg_lo:[0,1] neg_hi:[0,1]
	v_pk_add_f32 v[122:123], v[104:105], v[106:107] neg_lo:[0,1] neg_hi:[0,1]
	v_mfma_f32_32x32x16_bf16 v[80:95], v[204:207], v[216:219], v[80:95]
	v_lshlrev_b32_e32 v104, 16, v174
	v_and_b32_e32 v105, 0xffff0000, v174
	v_add_f32_e64 v106, v104, -v124
	v_add_f32_e64 v107, v105, -v125
	v_lshlrev_b32_e32 v104, 16, v175
	v_and_b32_e32 v105, 0xffff0000, v175
	v_pk_add_f32 v[124:125], v[104:105], v[126:127] neg_lo:[0,1] neg_hi:[0,1]
	s_waitcnt vmcnt(4)
	v_lshlrev_b32_e32 v104, 16, v176
	v_mfma_f32_32x32x16_bf16 v[80:95], v[212:215], v[224:227], v[80:95]
	v_and_b32_e32 v105, 0xffff0000, v176
	v_add_f32_e64 v126, v104, -v108
	v_add_f32_e64 v127, v105, -v109
	v_lshlrev_b32_e32 v104, 16, v177
	v_and_b32_e32 v105, 0xffff0000, v177
	v_pk_add_f32 v[96:97], v[188:189], v[96:97] neg_lo:[0,1] neg_hi:[0,1]
	v_pk_add_f32 v[116:117], v[186:187], v[116:117] neg_lo:[0,1] neg_hi:[0,1]
	v_pk_add_f32 v[144:145], v[104:105], v[110:111] neg_lo:[0,1] neg_hi:[0,1]
	v_mfma_f32_32x32x16_bf16 v[80:95], v[220:223], v[232:235], v[80:95]
	v_cvt_pk_bf16_f32 v108, v112, v113
	v_cvt_pk_bf16_f32 v109, v114, v115
	v_cvt_pk_bf16_f32 v110, v116, v117
	v_cvt_pk_bf16_f32 v111, v118, v119
	v_cvt_pk_bf16_f32 v104, v100, v101
	v_cvt_pk_bf16_f32 v105, v102, v103
	v_cvt_pk_bf16_f32 v106, v106, v107
	v_cvt_pk_bf16_f32 v107, v124, v125
	v_cvt_pk_bf16_f32 v100, v96, v97
	v_cvt_pk_bf16_f32 v101, v98, v99
	v_cvt_pk_bf16_f32 v102, v136, v137
	v_cvt_pk_bf16_f32 v103, v138, v139
	v_cvt_pk_bf16_f32 v96, v120, v121
	v_cvt_pk_bf16_f32 v97, v122, v123
	v_cvt_pk_bf16_f32 v98, v126, v127
	v_cvt_pk_bf16_f32 v99, v144, v145
	s_add_i32 s14, s9, 1
	s_cmp_lg_u32 s9, 63
	s_cselect_b32 s15, s14, 63
	v_mad_u64_u32 v[112:113], s[26:27], s15, v191, v[172:173]
	global_load_dwordx2 v[188:189], v[112:113], off
	global_load_dwordx2 v[182:183], v[112:113], off offset:512
	global_load_dwordx2 v[178:179], v[112:113], off offset:1024
	global_load_dwordx2 v[174:175], v[112:113], off offset:1536
	global_load_dwordx2 v[186:187], v[112:113], off offset:2048
	global_load_dwordx2 v[184:185], v[112:113], off offset:2560
	global_load_dwordx2 v[180:181], v[112:113], off offset:3072
	global_load_dwordx2 v[176:177], v[112:113], off offset:3584
	ds_read_b128 v[112:115], v198 offset:53312
	ds_read_b128 v[116:119], v198 offset:53344
	ds_read_b128 v[120:123], v198 offset:57920
	ds_read_b128 v[124:127], v198 offset:57952
	v_readlane_b32 s9, v197, s9
	s_waitcnt lgkmcnt(8)
	v_mfma_f32_32x32x16_bf16 v[80:95], v[152:155], v[236:239], v[80:95]
	s_waitcnt lgkmcnt(7)
	v_mfma_f32_32x32x16_bf16 v[64:79], v[148:151], v[108:111], v[64:79]
	v_mov_b32_e32 v144, s9
	v_mul_f32_e32 v0, v0, v144
	v_mul_f32_e32 v1, v1, v144
	v_mul_f32_e32 v2, v2, v144
	v_mul_f32_e32 v3, v3, v144
	v_mul_f32_e32 v4, v4, v144
	v_mul_f32_e32 v5, v5, v144
	s_waitcnt lgkmcnt(5)
	v_mfma_f32_32x32x16_bf16 v[80:95], v[140:143], v[108:111], v[80:95]
	v_mul_f32_e32 v6, v6, v144
	v_mul_f32_e32 v7, v7, v144
	v_mul_f32_e32 v8, v8, v144
	v_mul_f32_e32 v9, v9, v144
	v_mul_f32_e32 v10, v10, v144
	v_mul_f32_e32 v11, v11, v144
	v_mul_f32_e32 v12, v12, v144
	v_mul_f32_e32 v13, v13, v144
	v_mul_f32_e32 v14, v14, v144
	v_mul_f32_e32 v15, v15, v144
	v_mul_f32_e32 v16, v16, v144
	v_mul_f32_e32 v17, v17, v144
	v_mul_f32_e32 v18, v18, v144
	v_mfma_f32_32x32x16_bf16 v[64:79], v[132:135], v[104:107], v[64:79]
	v_mul_f32_e32 v19, v19, v144
	v_mul_f32_e32 v20, v20, v144
	v_mul_f32_e32 v21, v21, v144
	v_mul_f32_e32 v22, v22, v144
	v_mul_f32_e32 v23, v23, v144
	v_mul_f32_e32 v24, v24, v144
	v_mul_f32_e32 v25, v25, v144
	s_waitcnt lgkmcnt(4)
	v_mfma_f32_32x32x16_bf16 v[80:95], v[128:131], v[104:107], v[80:95]
	v_mul_f32_e32 v26, v26, v144
	v_mul_f32_e32 v27, v27, v144
	v_mul_f32_e32 v28, v28, v144
	v_mul_f32_e32 v29, v29, v144
	v_mul_f32_e32 v30, v30, v144
	v_mul_f32_e32 v31, v31, v144
	ds_read_b128 v[128:131], v198 offset:34816
	ds_read_b128 v[132:135], v198 offset:39424
	ds_read_b128 v[136:139], v198 offset:44032
	ds_read_b128 v[140:143], v198 offset:48640
	s_waitcnt lgkmcnt(7)
	v_mfma_f32_32x32x16_bf16 v[64:79], v[112:115], v[100:103], v[64:79]
	v_mul_f32_e32 v32, v32, v144
	v_mul_f32_e32 v33, v33, v144
	v_mul_f32_e32 v34, v34, v144
	v_mul_f32_e32 v35, v35, v144
	v_mul_f32_e32 v36, v36, v144
	v_mul_f32_e32 v37, v37, v144
	v_mul_f32_e32 v38, v38, v144
	s_waitcnt lgkmcnt(5)
	v_mfma_f32_32x32x16_bf16 v[80:95], v[120:123], v[100:103], v[80:95]
	v_mul_f32_e32 v39, v39, v144
	v_mul_f32_e32 v40, v40, v144
	v_mul_f32_e32 v41, v41, v144
	v_mul_f32_e32 v42, v42, v144
	v_mul_f32_e32 v43, v43, v144
	v_mul_f32_e32 v44, v44, v144
	v_mul_f32_e32 v45, v45, v144
	v_mul_f32_e32 v46, v46, v144
	v_mul_f32_e32 v47, v47, v144
	v_mul_f32_e32 v48, v48, v144
	v_mul_f32_e32 v49, v49, v144
	v_mul_f32_e32 v50, v50, v144
	v_mul_f32_e32 v51, v51, v144
	v_mfma_f32_32x32x16_bf16 v[64:79], v[116:119], v[96:99], v[64:79]
	v_mul_f32_e32 v52, v52, v144
	v_mul_f32_e32 v53, v53, v144
	v_mul_f32_e32 v54, v54, v144
	v_mul_f32_e32 v55, v55, v144
	v_mul_f32_e32 v56, v56, v144
	v_mul_f32_e32 v57, v57, v144
	v_mul_f32_e32 v58, v58, v144
	s_waitcnt lgkmcnt(4)
	v_mfma_f32_32x32x16_bf16 v[80:95], v[124:127], v[96:99], v[80:95]
	v_mul_f32_e32 v59, v59, v144
	v_mul_f32_e32 v60, v60, v144
	v_mul_f32_e32 v61, v61, v144
	v_mul_f32_e32 v62, v62, v144
	v_mul_f32_e32 v63, v63, v144
	ds_read_b128 v[112:115], v198 offset:34848
	ds_read_b128 v[116:119], v198 offset:39456
	ds_read_b128 v[120:123], v198 offset:44064
	ds_read_b128 v[124:127], v198 offset:48672
	s_waitcnt lgkmcnt(7)
	v_mfma_f32_32x32x16_bf16 v[0:15], v[128:131], v[108:111], v[0:15]
	s_waitcnt lgkmcnt(5)
	v_mfma_f32_32x32x16_bf16 v[32:47], v[136:139], v[108:111], v[32:47]
	ds_read_b128 v[128:131], v198 offset:34880
	ds_read_b128 v[136:139], v198 offset:39488
	ds_read_b128 v[144:147], v198 offset:44096
	ds_read_b128 v[148:151], v198 offset:48704
	s_waitcnt lgkmcnt(7)
	v_mfma_f32_32x32x16_bf16 v[0:15], v[112:115], v[104:107], v[0:15]
	s_waitcnt lgkmcnt(5)
	v_mfma_f32_32x32x16_bf16 v[32:47], v[120:123], v[104:107], v[32:47]
	ds_read_b128 v[112:115], v198 offset:34912
	ds_read_b128 v[120:123], v198 offset:39520
	ds_read_b128 v[152:155], v198 offset:44128
	ds_read_b128 v[156:159], v198 offset:48736
	s_waitcnt lgkmcnt(7)
	v_mfma_f32_32x32x16_bf16 v[0:15], v[128:131], v[100:103], v[0:15]
	s_waitcnt lgkmcnt(5)
	v_mfma_f32_32x32x16_bf16 v[32:47], v[144:147], v[100:103], v[32:47]
	s_waitcnt lgkmcnt(3)
	v_mfma_f32_32x32x16_bf16 v[0:15], v[112:115], v[96:99], v[0:15]
	s_waitcnt lgkmcnt(1)
	v_mfma_f32_32x32x16_bf16 v[32:47], v[152:155], v[96:99], v[32:47]
	v_mfma_f32_32x32x16_bf16 v[16:31], v[132:135], v[108:111], v[16:31]
	v_cvt_pk_bf16_f32 v64, v64, v65
	v_cvt_pk_bf16_f32 v65, v80, v81
	v_cvt_pk_bf16_f32 v66, v66, v67
	v_cvt_pk_bf16_f32 v67, v82, v83
	v_cvt_pk_bf16_f32 v68, v68, v69
	v_cvt_pk_bf16_f32 v69, v84, v85
	v_cvt_pk_bf16_f32 v70, v70, v71
	v_mfma_f32_32x32x16_bf16 v[16:31], v[116:119], v[104:107], v[16:31]
	v_cvt_pk_bf16_f32 v71, v86, v87
	v_cvt_pk_bf16_f32 v72, v72, v73
	v_cvt_pk_bf16_f32 v73, v88, v89
	v_cvt_pk_bf16_f32 v74, v74, v75
	v_cvt_pk_bf16_f32 v75, v90, v91
	v_cvt_pk_bf16_f32 v76, v76, v77
	v_cvt_pk_bf16_f32 v77, v92, v93
	v_mfma_f32_32x32x16_bf16 v[16:31], v[136:139], v[100:103], v[16:31]
	v_cvt_pk_bf16_f32 v78, v78, v79
	v_cvt_pk_bf16_f32 v79, v94, v95
	v_mfma_f32_32x32x16_bf16 v[16:31], v[120:123], v[96:99], v[16:31]
	v_mfma_f32_32x32x16_bf16 v[48:63], v[140:143], v[108:111], v[48:63]
	ds_write_b16 v195, v64
	ds_write_b16_d16_hi v195, v64 offset:80
	ds_write_b16 v195, v65 offset:2560
	ds_write_b16_d16_hi v195, v65 offset:2640
	ds_write_b16 v195, v66 offset:160
	ds_write_b16_d16_hi v195, v66 offset:240
	ds_write_b16 v195, v67 offset:2720
	ds_write_b16_d16_hi v195, v67 offset:2800
	ds_write_b16 v195, v68 offset:640
	ds_write_b16_d16_hi v195, v68 offset:720
	ds_write_b16 v195, v69 offset:3200
	ds_write_b16_d16_hi v195, v69 offset:3280
	ds_write_b16 v195, v70 offset:800
	ds_write_b16_d16_hi v195, v70 offset:880
	ds_write_b16 v195, v71 offset:3360
	ds_write_b16_d16_hi v195, v71 offset:3440
	ds_write_b16 v195, v72 offset:1280
	ds_write_b16_d16_hi v195, v72 offset:1360
	ds_write_b16 v195, v73 offset:3840
	ds_write_b16_d16_hi v195, v73 offset:3920
	ds_write_b16 v195, v74 offset:1440
	ds_write_b16_d16_hi v195, v74 offset:1520
	ds_write_b16 v195, v75 offset:4000
	ds_write_b16_d16_hi v195, v75 offset:4080
	ds_write_b16 v195, v76 offset:1920
	ds_write_b16_d16_hi v195, v76 offset:2000
	ds_write_b16 v195, v77 offset:4480
	ds_write_b16_d16_hi v195, v77 offset:4560
	ds_write_b16 v195, v78 offset:2080
	ds_write_b16_d16_hi v195, v78 offset:2160
	ds_write_b16 v195, v79 offset:4640
	ds_write_b16_d16_hi v195, v79 offset:4720
	ds_read_b128 v[64:67], v196
	ds_read_b128 v[68:71], v196 offset:1280
	ds_read_b128 v[72:75], v196 offset:2560
	ds_read_b128 v[76:79], v196 offset:3840
	s_ashr_i32 s9, s8, 31
	s_add_u32 s26, s80, s8
	s_addc_u32 s27, s81, s9
	v_mfma_f32_32x32x16_bf16 v[48:63], v[124:127], v[104:107], v[48:63]
	v_lshl_add_u64 v[80:81], s[26:27], 0, v[164:165]
	v_lshl_add_u64 v[86:87], s[26:27], 0, v[170:171]
	v_lshl_add_u64 v[82:83], s[26:27], 0, v[166:167]
	v_lshl_add_u64 v[84:85], s[26:27], 0, v[168:169]
	s_waitcnt lgkmcnt(3)
	global_store_dwordx4 v[80:81], v[64:67], off sc0 sc1
	s_waitcnt lgkmcnt(2)
	global_store_dwordx4 v[82:83], v[68:71], off sc0 sc1
	s_waitcnt lgkmcnt(1)
	global_store_dwordx4 v[84:85], v[72:75], off sc0 sc1
	s_waitcnt lgkmcnt(0)
	global_store_dwordx4 v[86:87], v[76:79], off sc0 sc1
	s_waitcnt lgkmcnt(0)
	v_mfma_f32_32x32x16_bf16 v[48:63], v[148:151], v[100:103], v[48:63]
	s_barrier
	s_add_i32 s8, s8, 0x20000
	s_cmp_eq_u32 s14, 64
	s_mov_b32 s9, s14
	v_mfma_f32_32x32x16_bf16 v[48:63], v[156:159], v[96:99], v[48:63]
	s_cbranch_scc0 .LBB0_501
	s_mov_b64 s[8:9], 0

.LBB0_505:
	s_bitcmp1_b32 s8, 0
	s_cselect_b32 s9, 0xf400, 0
	s_add_i32 s9, s9, 0
	v_add3_u32 v145, s9, v139, v140
	ds_read_b128 v[64:67], v145 offset:17408
	ds_read_b128 v[80:83], v145 offset:17440
	ds_read_b128 v[84:87], v145 offset:26112
	ds_read_b128 v[96:99], v145 offset:26144
	v_add3_u32 v191, s9, v141, v140
	v_cvt_pk_bf16_f32 v88, v0, v1
	v_cvt_pk_bf16_f32 v89, v2, v3
	v_cvt_pk_bf16_f32 v90, v4, v5
	v_cvt_pk_bf16_f32 v91, v6, v7
	s_waitcnt lgkmcnt(0)
	s_nop 0
	v_mfma_f32_32x32x16_bf16 v[64:79], v[64:67], v[88:91], 0
	ds_read_b128 v[92:95], v145 offset:17472
	ds_read_b128 v[100:103], v145 offset:26176
	v_cvt_pk_bf16_f32 v104, v8, v9
	v_cvt_pk_bf16_f32 v105, v10, v11
	v_cvt_pk_bf16_f32 v106, v12, v13
	v_cvt_pk_bf16_f32 v107, v14, v15
	s_nop 1
	v_mfma_f32_32x32x16_bf16 v[64:79], v[80:83], v[104:107], v[64:79]
	ds_read_b128 v[80:83], v145 offset:17504
	ds_read_b128 v[108:111], v145 offset:26208
	v_cvt_pk_bf16_f32 v146, v16, v17
	v_cvt_pk_bf16_f32 v147, v18, v19
	v_cvt_pk_bf16_f32 v148, v20, v21
	v_cvt_pk_bf16_f32 v149, v22, v23
	s_waitcnt lgkmcnt(0)
	s_nop 0
	v_mfma_f32_32x32x16_bf16 v[64:79], v[92:95], v[146:149], v[64:79]
	ds_read_b128 v[92:95], v145 offset:17536
	ds_read_b128 v[150:153], v145 offset:26240
	v_cvt_pk_bf16_f32 v154, v24, v25
	v_cvt_pk_bf16_f32 v155, v26, v27
	v_cvt_pk_bf16_f32 v156, v28, v29
	v_cvt_pk_bf16_f32 v157, v30, v31
	s_nop 1
	v_mfma_f32_32x32x16_bf16 v[64:79], v[80:83], v[154:157], v[64:79]
	ds_read_b128 v[80:83], v145 offset:17568
	ds_read_b128 v[158:161], v145 offset:26272
	v_cvt_pk_bf16_f32 v162, v32, v33
	v_cvt_pk_bf16_f32 v163, v34, v35
	v_cvt_pk_bf16_f32 v164, v36, v37
	v_cvt_pk_bf16_f32 v165, v38, v39
	s_waitcnt lgkmcnt(0)
	s_nop 0
	v_mfma_f32_32x32x16_bf16 v[64:79], v[92:95], v[162:165], v[64:79]
	ds_read_b128 v[92:95], v145 offset:17600
	ds_read_b128 v[166:169], v145 offset:26304
	v_cvt_pk_bf16_f32 v170, v40, v41
	v_cvt_pk_bf16_f32 v171, v42, v43
	v_cvt_pk_bf16_f32 v172, v44, v45
	v_cvt_pk_bf16_f32 v173, v46, v47
	s_nop 1
	v_mfma_f32_32x32x16_bf16 v[64:79], v[80:83], v[170:173], v[64:79]
	ds_read_b128 v[80:83], v145 offset:17632
	s_waitcnt vmcnt(4)
	ds_read_b128 v[174:177], v145 offset:26336
	v_cvt_pk_bf16_f32 v178, v48, v49
	v_cvt_pk_bf16_f32 v179, v50, v51
	v_cvt_pk_bf16_f32 v180, v52, v53
	v_cvt_pk_bf16_f32 v181, v54, v55
	s_waitcnt lgkmcnt(3)
	s_nop 0
	v_mfma_f32_32x32x16_bf16 v[64:79], v[92:95], v[178:181], v[64:79]
	ds_read_b128 v[182:185], v191 offset:53248
	ds_read_b128 v[186:189], v191 offset:53280
	ds_read_b128 v[192:195], v191 offset:57856
	ds_read_b128 v[196:199], v191 offset:57888
	v_cvt_pk_bf16_f32 v200, v56, v57
	v_cvt_pk_bf16_f32 v201, v58, v59
	v_cvt_pk_bf16_f32 v202, v60, v61
	v_cvt_pk_bf16_f32 v203, v62, v63
	s_waitcnt lgkmcnt(5)
	s_nop 0
	v_mfma_f32_32x32x16_bf16 v[64:79], v[80:83], v[200:203], v[64:79]
	v_mfma_f32_32x32x16_bf16 v[80:95], v[84:87], v[88:91], 0
	v_lshlrev_b32_e32 v145, 16, v136
	v_and_b32_e32 v136, 0xffff0000, v136
	v_lshlrev_b32_e32 v204, 16, v137
	v_and_b32_e32 v137, 0xffff0000, v137
	v_lshlrev_b32_e32 v205, 16, v134
	v_and_b32_e32 v134, 0xffff0000, v134
	v_lshlrev_b32_e32 v206, 16, v135
	v_mfma_f32_32x32x16_bf16 v[80:95], v[96:99], v[104:107], v[80:95]
	v_and_b32_e32 v135, 0xffff0000, v135
	v_lshlrev_b32_e32 v207, 16, v130
	v_and_b32_e32 v130, 0xffff0000, v130
	v_lshlrev_b32_e32 v208, 16, v131
	v_and_b32_e32 v131, 0xffff0000, v131
	v_lshlrev_b32_e32 v96, 16, v132
	v_and_b32_e32 v97, 0xffff0000, v132
	v_mfma_f32_32x32x16_bf16 v[80:95], v[100:103], v[146:149], v[80:95]
	v_lshlrev_b32_e32 v98, 16, v133
	v_and_b32_e32 v99, 0xffff0000, v133
	v_lshlrev_b32_e32 v104, 16, v126
	v_and_b32_e32 v105, 0xffff0000, v126
	v_lshlrev_b32_e32 v106, 16, v127
	v_and_b32_e32 v100, 0xffff0000, v127
	v_lshlrev_b32_e32 v126, 16, v128
	v_mfma_f32_32x32x16_bf16 v[80:95], v[108:111], v[154:157], v[80:95]
	v_and_b32_e32 v127, 0xffff0000, v128
	v_lshlrev_b32_e32 v128, 16, v129
	v_and_b32_e32 v129, 0xffff0000, v129
	v_lshlrev_b32_e32 v101, 16, v122
	v_and_b32_e32 v102, 0xffff0000, v122
	v_lshlrev_b32_e32 v103, 16, v123
	v_and_b32_e32 v107, 0xffff0000, v123
	v_mfma_f32_32x32x16_bf16 v[80:95], v[150:153], v[162:165], v[80:95]
	v_lshlrev_b32_e32 v122, 16, v124
	v_and_b32_e32 v123, 0xffff0000, v124
	v_lshlrev_b32_e32 v124, 16, v125
	v_and_b32_e32 v125, 0xffff0000, v125
	v_cvt_pk_bf16_f32 v108, v145, v136
	v_cvt_pk_bf16_f32 v109, v204, v137
	v_cvt_pk_bf16_f32 v110, v207, v130
	v_mfma_f32_32x32x16_bf16 v[80:95], v[158:161], v[170:173], v[80:95]
	v_cvt_pk_bf16_f32 v111, v208, v131
	v_cvt_pk_bf16_f32 v104, v104, v105
	v_cvt_pk_bf16_f32 v105, v106, v100
	v_cvt_pk_bf16_f32 v106, v101, v102
	v_cvt_pk_bf16_f32 v107, v103, v107
	v_cvt_pk_bf16_f32 v100, v205, v134
	v_cvt_pk_bf16_f32 v101, v206, v135
	v_cvt_pk_bf16_f32 v102, v96, v97
	v_cvt_pk_bf16_f32 v103, v98, v99
	v_cvt_pk_bf16_f32 v96, v126, v127
	v_cvt_pk_bf16_f32 v97, v128, v129
	v_cvt_pk_bf16_f32 v98, v122, v123
	v_cvt_pk_bf16_f32 v99, v124, v125
	v_mfma_f32_32x32x16_bf16 v[80:95], v[166:169], v[178:181], v[80:95]
	s_add_i32 s9, s8, 1
	s_cmp_lg_u32 s8, 63
	s_cselect_b32 s8, s9, 63
	v_mad_u64_u32 v[124:125], s[12:13], s8, v144, v[114:115]
	global_load_dwordx2 v[136:137], v[124:125], off
	global_load_dwordx2 v[130:131], v[124:125], off offset:512
	global_load_dwordx2 v[126:127], v[124:125], off offset:1024
	global_load_dwordx2 v[122:123], v[124:125], off offset:1536
	global_load_dwordx2 v[134:135], v[124:125], off offset:2048
	global_load_dwordx2 v[132:133], v[124:125], off offset:2560
	global_load_dwordx2 v[128:129], v[124:125], off offset:3072
	s_nop 0
	global_load_dwordx2 v[124:125], v[124:125], off offset:3584
	ds_read_b128 v[146:149], v191 offset:53312
	ds_read_b128 v[150:153], v191 offset:53344
	ds_read_b128 v[154:157], v191 offset:57920
	ds_read_b128 v[158:161], v191 offset:57952
	s_waitcnt lgkmcnt(8)
	v_mfma_f32_32x32x16_bf16 v[80:95], v[174:177], v[200:203], v[80:95]
	s_waitcnt lgkmcnt(7)
	v_mfma_f32_32x32x16_bf16 v[64:79], v[182:185], v[108:111], v[64:79]
	v_mul_f32_e32 v0, v0, v138
	v_mul_f32_e32 v1, v1, v138
	v_mul_f32_e32 v2, v2, v138
	v_mul_f32_e32 v3, v3, v138
	v_mul_f32_e32 v4, v4, v138
	v_mul_f32_e32 v5, v5, v138
	v_mul_f32_e32 v6, v6, v138
	s_waitcnt lgkmcnt(5)
	v_mfma_f32_32x32x16_bf16 v[80:95], v[192:195], v[108:111], v[80:95]
	v_mul_f32_e32 v7, v7, v138
	v_mul_f32_e32 v8, v8, v138
	v_mul_f32_e32 v9, v9, v138
	v_mul_f32_e32 v10, v10, v138
	v_mul_f32_e32 v11, v11, v138
	v_mul_f32_e32 v12, v12, v138
	v_mul_f32_e32 v13, v13, v138
	v_mul_f32_e32 v14, v14, v138
	v_mul_f32_e32 v15, v15, v138
	v_mul_f32_e32 v16, v16, v138
	v_mul_f32_e32 v17, v17, v138
	v_mul_f32_e32 v18, v18, v138
	v_mul_f32_e32 v19, v19, v138
	v_mfma_f32_32x32x16_bf16 v[64:79], v[186:189], v[104:107], v[64:79]
	v_mul_f32_e32 v20, v20, v138
	v_mul_f32_e32 v21, v21, v138
	v_mul_f32_e32 v22, v22, v138
	v_mul_f32_e32 v23, v23, v138
	v_mul_f32_e32 v24, v24, v138
	v_mul_f32_e32 v25, v25, v138
	v_mul_f32_e32 v26, v26, v138
	s_waitcnt lgkmcnt(4)
	v_mfma_f32_32x32x16_bf16 v[80:95], v[196:199], v[104:107], v[80:95]
	v_mul_f32_e32 v27, v27, v138
	v_mul_f32_e32 v28, v28, v138
	v_mul_f32_e32 v29, v29, v138
	v_mul_f32_e32 v30, v30, v138
	v_mul_f32_e32 v31, v31, v138
	ds_read_b128 v[162:165], v191 offset:34816
	ds_read_b128 v[166:169], v191 offset:39424
	ds_read_b128 v[170:173], v191 offset:44032
	ds_read_b128 v[174:177], v191 offset:48640
	s_waitcnt lgkmcnt(7)
	v_mfma_f32_32x32x16_bf16 v[64:79], v[146:149], v[100:103], v[64:79]
	v_mul_f32_e32 v32, v32, v138
	v_mul_f32_e32 v33, v33, v138
	v_mul_f32_e32 v34, v34, v138
	v_mul_f32_e32 v35, v35, v138
	v_mul_f32_e32 v36, v36, v138
	v_mul_f32_e32 v37, v37, v138
	v_mul_f32_e32 v38, v38, v138
	s_waitcnt lgkmcnt(5)
	v_mfma_f32_32x32x16_bf16 v[80:95], v[154:157], v[100:103], v[80:95]
	v_mul_f32_e32 v39, v39, v138
	v_mul_f32_e32 v40, v40, v138
	v_mul_f32_e32 v41, v41, v138
	v_mul_f32_e32 v42, v42, v138
	v_mul_f32_e32 v43, v43, v138
	v_mul_f32_e32 v44, v44, v138
	v_mul_f32_e32 v45, v45, v138
	v_mul_f32_e32 v46, v46, v138
	v_mul_f32_e32 v47, v47, v138
	v_mul_f32_e32 v48, v48, v138
	v_mul_f32_e32 v49, v49, v138
	v_mul_f32_e32 v50, v50, v138
	v_mul_f32_e32 v51, v51, v138
	v_mfma_f32_32x32x16_bf16 v[64:79], v[150:153], v[96:99], v[64:79]
	v_mul_f32_e32 v52, v52, v138
	v_mul_f32_e32 v53, v53, v138
	v_mul_f32_e32 v54, v54, v138
	v_mul_f32_e32 v55, v55, v138
	v_mul_f32_e32 v56, v56, v138
	v_mul_f32_e32 v57, v57, v138
	v_mul_f32_e32 v58, v58, v138
	s_waitcnt lgkmcnt(4)
	v_mfma_f32_32x32x16_bf16 v[80:95], v[158:161], v[96:99], v[80:95]
	v_mul_f32_e32 v59, v59, v138
	v_mul_f32_e32 v60, v60, v138
	v_mul_f32_e32 v61, v61, v138
	v_mul_f32_e32 v62, v62, v138
	v_mul_f32_e32 v63, v63, v138
	ds_read_b128 v[146:149], v191 offset:34848
	ds_read_b128 v[150:153], v191 offset:39456
	ds_read_b128 v[154:157], v191 offset:44064
	ds_read_b128 v[158:161], v191 offset:48672
	s_waitcnt lgkmcnt(7)
	v_mfma_f32_32x32x16_bf16 v[0:15], v[162:165], v[108:111], v[0:15]
	s_waitcnt lgkmcnt(5)
	v_mfma_f32_32x32x16_bf16 v[32:47], v[170:173], v[108:111], v[32:47]
	ds_read_b128 v[162:165], v191 offset:34880
	ds_read_b128 v[170:173], v191 offset:39488
	ds_read_b128 v[178:181], v191 offset:44096
	ds_read_b128 v[182:185], v191 offset:48704
	s_waitcnt lgkmcnt(7)
	v_mfma_f32_32x32x16_bf16 v[0:15], v[146:149], v[104:107], v[0:15]
	s_waitcnt lgkmcnt(5)
	v_mfma_f32_32x32x16_bf16 v[32:47], v[154:157], v[104:107], v[32:47]
	ds_read_b128 v[146:149], v191 offset:34912
	ds_read_b128 v[154:157], v191 offset:39520
	ds_read_b128 v[186:189], v191 offset:44128
	ds_read_b128 v[192:195], v191 offset:48736
	s_waitcnt lgkmcnt(7)
	v_mfma_f32_32x32x16_bf16 v[0:15], v[162:165], v[100:103], v[0:15]
	s_waitcnt lgkmcnt(5)
	v_mfma_f32_32x32x16_bf16 v[32:47], v[178:181], v[100:103], v[32:47]
	s_waitcnt lgkmcnt(3)
	v_mfma_f32_32x32x16_bf16 v[0:15], v[146:149], v[96:99], v[0:15]
	s_waitcnt lgkmcnt(1)
	v_mfma_f32_32x32x16_bf16 v[32:47], v[186:189], v[96:99], v[32:47]
	v_mfma_f32_32x32x16_bf16 v[16:31], v[166:169], v[108:111], v[16:31]
	v_cvt_pk_bf16_f32 v64, v64, v65
	v_cvt_pk_bf16_f32 v65, v80, v81
	v_cvt_pk_bf16_f32 v66, v66, v67
	v_cvt_pk_bf16_f32 v67, v82, v83
	v_cvt_pk_bf16_f32 v68, v68, v69
	v_cvt_pk_bf16_f32 v69, v84, v85
	v_cvt_pk_bf16_f32 v70, v70, v71
	v_mfma_f32_32x32x16_bf16 v[16:31], v[150:153], v[104:107], v[16:31]
	v_cvt_pk_bf16_f32 v71, v86, v87
	v_cvt_pk_bf16_f32 v72, v72, v73
	v_cvt_pk_bf16_f32 v73, v88, v89
	v_cvt_pk_bf16_f32 v74, v74, v75
	v_cvt_pk_bf16_f32 v75, v90, v91
	v_cvt_pk_bf16_f32 v76, v76, v77
	v_cvt_pk_bf16_f32 v77, v92, v93
	v_mfma_f32_32x32x16_bf16 v[16:31], v[170:173], v[100:103], v[16:31]
	v_cvt_pk_bf16_f32 v78, v78, v79
	v_cvt_pk_bf16_f32 v79, v94, v95
	v_mfma_f32_32x32x16_bf16 v[16:31], v[154:157], v[96:99], v[16:31]
	v_mfma_f32_32x32x16_bf16 v[48:63], v[174:177], v[108:111], v[48:63]
	ds_write_b16 v142, v64
	ds_write_b16_d16_hi v142, v64 offset:80
	ds_write_b16 v142, v65 offset:2560
	ds_write_b16_d16_hi v142, v65 offset:2640
	ds_write_b16 v142, v66 offset:160
	ds_write_b16_d16_hi v142, v66 offset:240
	ds_write_b16 v142, v67 offset:2720
	ds_write_b16_d16_hi v142, v67 offset:2800
	ds_write_b16 v142, v68 offset:640
	ds_write_b16_d16_hi v142, v68 offset:720
	ds_write_b16 v142, v69 offset:3200
	ds_write_b16_d16_hi v142, v69 offset:3280
	ds_write_b16 v142, v70 offset:800
	ds_write_b16_d16_hi v142, v70 offset:880
	ds_write_b16 v142, v71 offset:3360
	ds_write_b16_d16_hi v142, v71 offset:3440
	ds_write_b16 v142, v72 offset:1280
	ds_write_b16_d16_hi v142, v72 offset:1360
	ds_write_b16 v142, v73 offset:3840
	ds_write_b16_d16_hi v142, v73 offset:3920
	ds_write_b16 v142, v74 offset:1440
	ds_write_b16_d16_hi v142, v74 offset:1520
	ds_write_b16 v142, v75 offset:4000
	ds_write_b16_d16_hi v142, v75 offset:4080
	ds_write_b16 v142, v76 offset:1920
	ds_write_b16_d16_hi v142, v76 offset:2000
	ds_write_b16 v142, v77 offset:4480
	ds_write_b16_d16_hi v142, v77 offset:4560
	ds_write_b16 v142, v78 offset:2080
	ds_write_b16_d16_hi v142, v78 offset:2160
	ds_write_b16 v142, v79 offset:4640
	ds_write_b16_d16_hi v142, v79 offset:4720
	ds_read_b128 v[64:67], v143
	ds_read_b128 v[68:71], v143 offset:1280
	ds_read_b128 v[72:75], v143 offset:2560
	ds_read_b128 v[76:79], v143 offset:3840
	s_ashr_i32 s8, s3, 31
	s_add_u32 s12, s80, s3
	s_addc_u32 s13, s81, s8
	v_mfma_f32_32x32x16_bf16 v[48:63], v[158:161], v[104:107], v[48:63]
	v_lshl_add_u64 v[80:81], s[12:13], 0, v[112:113]
	v_lshl_add_u64 v[86:87], s[12:13], 0, v[120:121]
	v_lshl_add_u64 v[82:83], s[12:13], 0, v[116:117]
	v_lshl_add_u64 v[84:85], s[12:13], 0, v[118:119]
	s_waitcnt lgkmcnt(3)
	global_store_dwordx4 v[80:81], v[64:67], off sc0 sc1
	s_waitcnt lgkmcnt(2)
	global_store_dwordx4 v[82:83], v[68:71], off sc0 sc1
	s_waitcnt lgkmcnt(1)
	global_store_dwordx4 v[84:85], v[72:75], off sc0 sc1
	s_waitcnt lgkmcnt(0)
	global_store_dwordx4 v[86:87], v[76:79], off sc0 sc1
	s_waitcnt lgkmcnt(0)
	v_mfma_f32_32x32x16_bf16 v[48:63], v[182:185], v[100:103], v[48:63]
	s_barrier
	s_add_i32 s3, s3, 0x20000
	s_cmp_eq_u32 s9, 64
	s_mov_b32 s8, s9
	v_mfma_f32_32x32x16_bf16 v[48:63], v[192:195], v[96:99], v[48:63]
	s_cbranch_scc0 .LBB0_505
.LBB0_506:
	s_waitcnt vmcnt(0)
	v_mov_b32_e32 v242, 63
	s_mov_b64 exec, 1
	global_store_dword v241, v242, s[98:99] sc0 sc1
	s_mov_b64 exec, -1
	s_setprio 0
	s_mov_b64 s[8:9], 0
.LBB0_507:
	s_and_b64 vcc, exec, s[8:9]
	s_cbranch_vccz .LBB0_520
	s_add_u32 s98, s54, 0x1ec04000
	s_addc_u32 s99, s55, 0
	s_lshl_b32 s100, s2, 8
	s_add_u32 s98, s98, s100
	s_addc_u32 s99, s99, 0
	s_sub_u32 s100, s95, 4
	s_lshl_b32 s100, s100, 2
	s_add_u32 s98, s98, s100
	s_addc_u32 s99, s99, 0
	v_mov_b32_e32 v238, 0
	s_and_b64 s[8:9], s[6:7], exec
	s_movk_i32 s8, 0x4000
	s_cselect_b32 s14, s8, 0x8000
	s_mov_b32 s8, 0xc000
	s_mov_b32 s3, 0xe000
	s_cselect_b32 s15, 0x8000, s8
	s_mov_b32 s8, 0x10000
	s_cselect_b32 s3, s3, 0x12000
	s_cselect_b32 s26, 0xc000, s8
	s_and_b32 s8, s85, 0xffffffc0
	s_addk_i32 s8, 0xff00
	s_waitcnt vmcnt(0)
	v_add_u32_e32 v122, s8, v190
	s_add_u32 s8, s16, 0x4000
	s_addc_u32 s9, s17, 0
	s_add_u32 s12, s16, 0x8000
	s_mov_b32 s27, 0
	s_addc_u32 s13, s17, 0
	s_and_b64 vcc, exec, s[0:1]
	s_mov_b64 s[0:1], -1
	s_cbranch_vccnz .LBB0_514
	v_mov_b32_e32 v56, v122
	s_and_b64 s[0:1], s[6:7], exec
	v_lshlrev_b32_e32 v112, 4, v56
	v_ashrrev_i32_e32 v113, 31, v112
	s_cselect_b32 s6, 0, 0x4000
	s_add_u32 s0, s16, 0xc000
	v_lshl_add_u64 v[0:1], s[8:9], 0, v[112:113]
	s_addc_u32 s1, s17, 0
	global_load_dwordx4 v[0:3], v[0:1], off
	v_lshl_add_u64 v[4:5], s[12:13], 0, v[112:113]
	v_add_u32_e32 v114, 0x1000, v112
	global_load_dwordx4 v[4:7], v[4:5], off
	v_lshl_add_u64 v[8:9], s[0:1], 0, v[112:113]
	v_ashrrev_i32_e32 v115, 31, v114
	global_load_dwordx4 v[8:11], v[8:9], off
	v_lshl_add_u64 v[12:13], s[8:9], 0, v[114:115]
	global_load_dwordx4 v[12:15], v[12:13], off
	v_lshl_add_u64 v[16:17], s[12:13], 0, v[114:115]
	v_add_u32_e32 v116, 0x2000, v112
	global_load_dwordx4 v[16:19], v[16:17], off
	v_lshl_add_u64 v[20:21], s[0:1], 0, v[114:115]
	v_ashrrev_i32_e32 v117, 31, v116
	global_load_dwordx4 v[20:23], v[20:21], off
	v_lshl_add_u64 v[24:25], s[8:9], 0, v[116:117]
	global_load_dwordx4 v[24:27], v[24:25], off
	v_lshl_add_u64 v[28:29], s[12:13], 0, v[116:117]
	v_add_u32_e32 v118, 0x3000, v112
	global_load_dwordx4 v[28:31], v[28:29], off
	v_lshl_add_u64 v[32:33], s[0:1], 0, v[116:117]
	v_ashrrev_i32_e32 v119, 31, v118
	global_load_dwordx4 v[32:35], v[32:33], off
	v_lshl_add_u64 v[36:37], s[8:9], 0, v[118:119]
	v_add_u32_e32 v57, 0x100, v56
	global_load_dwordx4 v[36:39], v[36:37], off
	v_lshl_add_u64 v[40:41], s[12:13], 0, v[118:119]
	v_lshl_add_u64 v[44:45], s[0:1], 0, v[118:119]
	s_add_u32 s0, s16, 0x10000
	v_lshlrev_b32_e32 v120, 4, v57
	global_load_dwordx4 v[40:43], v[40:41], off
	s_addc_u32 s1, s17, 0
	v_ashrrev_i32_e32 v121, 31, v120
	global_load_dwordx4 v[44:47], v[44:45], off
	v_lshl_add_u64 v[48:49], s[0:1], 0, v[112:113]
	v_lshl_add_u64 v[52:53], s[0:1], 0, v[120:121]
	v_and_b32_e32 v141, 0xf0, v112
	v_lshrrev_b32_e32 v60, 4, v56
	s_movk_i32 s0, 0x110
	global_load_dwordx4 v[48:51], v[48:49], off
	v_add_u32_e32 v58, 0, v141
	v_mul_lo_u32 v123, v60, s0
	global_load_dwordx4 v[52:55], v[52:53], off
	v_add_u32_e32 v124, v58, v123
	s_waitcnt vmcnt(0)
	ds_write_b128 v124, v[0:3]
	ds_write_b128 v124, v[4:7] offset:17408
	v_lshrrev_b32_e32 v0, 3, v56
	s_movk_i32 s1, 0x90
	v_mul_lo_u32 v125, v0, s1
	v_lshrrev_b32_e32 v0, 4, v57
	v_mul_lo_u32 v127, v0, s0
	v_lshrrev_b32_e32 v0, 3, v57
	v_mul_lo_u32 v129, v0, s1
	v_add_u32_e32 v0, 0x200, v56
	v_lshrrev_b32_e32 v1, 4, v0
	v_lshrrev_b32_e32 v0, 3, v0
	v_mul_lo_u32 v133, v0, s1
	v_add_u32_e32 v0, 0x300, v56
	v_mul_lo_u32 v131, v1, s0
	v_lshrrev_b32_e32 v1, 4, v0
	v_mul_lo_u32 v135, v1, s0
	v_lshrrev_b32_e32 v0, 3, v0
	s_add_u32 s0, s16, 0x16000
	v_and_b32_e32 v144, 0x70, v112
	v_mul_lo_u32 v137, v0, s1
	v_add_u32_e32 v0, 0, v125
	s_addc_u32 s1, s17, 0
	v_add_u32_e32 v59, 0, v144
	v_add_u32_e32 v139, v0, v144
	v_add_u32_e32 v0, 0, v129
	s_add_u32 s28, s16, 0x1a000
	v_add_u32_e32 v126, v59, v125
	v_add_u32_e32 v128, v58, v127
	v_add_u32_e32 v130, v59, v129
	v_add_u32_e32 v132, v58, v131
	v_add_u32_e32 v134, v59, v133
	v_add_u32_e32 v136, v58, v135
	v_add_u32_e32 v138, v59, v137
	v_add_u32_e32 v140, v0, v144
	s_addc_u32 s29, s17, 0
	ds_write_b128 v126, v[8:11] offset:34816
	ds_write_b128 v128, v[12:15]
	ds_write_b128 v128, v[16:19] offset:17408
	ds_write_b128 v130, v[20:23] offset:34816
	ds_write_b128 v132, v[24:27]
	ds_write_b128 v132, v[28:31] offset:17408
	ds_write_b128 v134, v[32:35] offset:34816
	ds_write_b128 v136, v[36:39]
	ds_write_b128 v136, v[40:43] offset:17408
	ds_write_b128 v138, v[44:47] offset:34816
	ds_write_b128 v139, v[48:51] offset:53248
	ds_write_b128 v140, v[52:55] offset:53248
	s_add_u32 s34, s16, 0x1e000
	v_lshl_add_u64 v[0:1], s[0:1], 0, v[112:113]
	s_addc_u32 s35, s17, 0
	global_load_dwordx4 v[0:3], v[0:1], off
	v_lshl_add_u64 v[4:5], s[28:29], 0, v[112:113]
	global_load_dwordx4 v[4:7], v[4:5], off
	v_lshl_add_u64 v[8:9], s[34:35], 0, v[112:113]
	global_load_dwordx4 v[8:11], v[8:9], off
	v_lshl_add_u64 v[12:13], s[0:1], 0, v[114:115]
	global_load_dwordx4 v[12:15], v[12:13], off
	v_lshl_add_u64 v[16:17], s[28:29], 0, v[114:115]
	global_load_dwordx4 v[16:19], v[16:17], off
	v_lshl_add_u64 v[20:21], s[34:35], 0, v[114:115]
	global_load_dwordx4 v[20:23], v[20:21], off
	v_lshl_add_u64 v[24:25], s[0:1], 0, v[116:117]
	global_load_dwordx4 v[24:27], v[24:25], off
	v_lshl_add_u64 v[28:29], s[28:29], 0, v[116:117]
	global_load_dwordx4 v[28:31], v[28:29], off
	v_lshl_add_u64 v[32:33], s[34:35], 0, v[116:117]
	v_lshl_add_u64 v[36:37], s[0:1], 0, v[118:119]
	s_add_u32 s0, s16, 0x22000
	global_load_dwordx4 v[32:35], v[32:33], off
	s_addc_u32 s1, s17, 0
	global_load_dwordx4 v[36:39], v[36:37], off
	v_lshl_add_u64 v[40:41], s[28:29], 0, v[118:119]
	v_lshl_add_u64 v[48:49], s[0:1], 0, v[112:113]
	v_lshl_add_u64 v[52:53], s[0:1], 0, v[120:121]
	s_add_u32 s0, s16, 0x28000
	global_load_dwordx4 v[40:43], v[40:41], off
	v_lshl_add_u64 v[44:45], s[34:35], 0, v[118:119]
	s_addc_u32 s1, s17, 0
	global_load_dwordx4 v[44:47], v[44:45], off
	s_add_u32 s28, s16, 0x2c000
	global_load_dwordx4 v[48:51], v[48:49], off
	s_addc_u32 s29, s17, 0
	global_load_dwordx4 v[56:59], v[52:53], off
	s_mov_b64 exec, 1
	v_mov_b32_e32 v239, 0
	global_store_dword v238, v239, s[98:99] sc0 sc1
	s_mov_b64 exec, -1
	s_add_u32 s34, s16, 0x30000
	v_lshl_add_u64 v[52:53], s[0:1], 0, v[112:113]
	s_addc_u32 s35, s17, 0
	global_load_dwordx4 v[52:55], v[52:53], off
	v_lshl_add_u64 v[60:61], s[28:29], 0, v[112:113]
	global_load_dwordx4 v[60:63], v[60:61], off
	v_lshl_add_u64 v[64:65], s[34:35], 0, v[112:113]
	global_load_dwordx4 v[64:67], v[64:65], off
	v_lshl_add_u64 v[68:69], s[0:1], 0, v[114:115]
	global_load_dwordx4 v[68:71], v[68:69], off
	v_lshl_add_u64 v[72:73], s[28:29], 0, v[114:115]
	global_load_dwordx4 v[72:75], v[72:73], off
	v_lshl_add_u64 v[76:77], s[34:35], 0, v[114:115]
	global_load_dwordx4 v[76:79], v[76:77], off
	v_lshl_add_u64 v[80:81], s[0:1], 0, v[116:117]
	global_load_dwordx4 v[80:83], v[80:81], off
	v_lshl_add_u64 v[84:85], s[28:29], 0, v[116:117]
	global_load_dwordx4 v[84:87], v[84:85], off
	v_lshl_add_u64 v[88:89], s[34:35], 0, v[116:117]
	global_load_dwordx4 v[88:91], v[88:89], off
	v_lshl_add_u64 v[92:93], s[0:1], 0, v[118:119]
	global_load_dwordx4 v[92:95], v[92:93], off
	v_lshl_add_u64 v[96:97], s[28:29], 0, v[118:119]
	s_add_u32 s0, s16, 0x34000
	global_load_dwordx4 v[96:99], v[96:97], off
	v_lshl_add_u64 v[100:101], s[34:35], 0, v[118:119]
	s_addc_u32 s1, s17, 0
	global_load_dwordx4 v[100:103], v[100:101], off
	v_lshl_add_u64 v[104:105], s[0:1], 0, v[112:113]
	global_load_dwordx4 v[104:107], v[104:105], off
	v_lshl_add_u64 v[108:109], s[0:1], 0, v[120:121]
	s_add_i32 s0, 0, 0x13800
	global_load_dwordx4 v[108:111], v[108:109], off
	v_add_u32_e32 v141, s0, v141
	s_add_i32 s0, 0, 0x17c00
	s_waitcnt lgkmcnt(0)
	s_barrier
	v_add_u32_e32 v142, s0, v144
	s_add_i32 s0, 0, 0x1c400
	v_add_u32_e32 v143, s0, v125
	v_add_u32_e32 v145, s0, v129
	v_add_u32_e32 v143, v143, v144
	v_add_u32_e32 v144, v145, v144
	s_branch .LBB0_511

.LBB0_511:
	s_min_u32 s0, s27, 60
	s_waitcnt vmcnt(15)
	s_mov_b64 exec, 1
	v_mov_b32_e32 v239, s27
	global_store_dword v238, v239, s[98:99] sc0 sc1
	s_mov_b64 exec, -1
.Lpf_nopub_a1:
	ds_write_b128 v124, v[0:3] offset:62464
	v_add_u32_e32 v0, v141, v123
	s_add_i32 s0, s0, 3
	ds_write_b128 v0, v[4:7]
	v_add_u32_e32 v0, v142, v125
	s_mul_i32 s0, s3, s0
	ds_write_b128 v0, v[8:11]
	ds_write_b128 v128, v[12:15] offset:62464
	v_add_u32_e32 v0, v141, v127
	s_add_u32 s7, s16, s0
	ds_write_b128 v0, v[16:19]
	v_add_u32_e32 v0, v142, v129
	s_addc_u32 s38, s17, 0
	ds_write_b128 v0, v[20:23]
	ds_write_b128 v132, v[24:27] offset:62464
	v_add_u32_e32 v0, v141, v131
	s_add_u32 s0, s7, s6
	ds_write_b128 v0, v[28:31]
	v_add_u32_e32 v0, v142, v133
	s_addc_u32 s1, s38, 0
	ds_write_b128 v0, v[32:35]
	ds_write_b128 v136, v[36:39] offset:62464
	v_add_u32_e32 v0, v141, v135
	s_add_u32 s28, s7, s14
	ds_write_b128 v0, v[40:43]
	v_add_u32_e32 v0, v142, v137
	s_addc_u32 s29, s38, 0
	ds_write_b128 v0, v[44:47]
	ds_write_b128 v143, v[48:51]
	ds_write_b128 v144, v[56:59]
	s_add_u32 s34, s7, s15
	v_lshl_add_u64 v[0:1], s[0:1], 0, v[112:113]
	s_addc_u32 s35, s38, 0
	global_load_dwordx4 v[0:3], v[0:1], off
	v_lshl_add_u64 v[4:5], s[28:29], 0, v[112:113]
	global_load_dwordx4 v[4:7], v[4:5], off
	v_lshl_add_u64 v[8:9], s[34:35], 0, v[112:113]
	global_load_dwordx4 v[8:11], v[8:9], off
	v_lshl_add_u64 v[12:13], s[0:1], 0, v[114:115]
	global_load_dwordx4 v[12:15], v[12:13], off
	v_lshl_add_u64 v[16:17], s[28:29], 0, v[114:115]
	global_load_dwordx4 v[16:19], v[16:17], off
	v_lshl_add_u64 v[20:21], s[34:35], 0, v[114:115]
	global_load_dwordx4 v[20:23], v[20:21], off
	v_lshl_add_u64 v[24:25], s[0:1], 0, v[116:117]
	global_load_dwordx4 v[24:27], v[24:25], off
	v_lshl_add_u64 v[28:29], s[28:29], 0, v[116:117]
	global_load_dwordx4 v[28:31], v[28:29], off
	v_lshl_add_u64 v[32:33], s[34:35], 0, v[116:117]
	global_load_dwordx4 v[32:35], v[32:33], off
	v_lshl_add_u64 v[36:37], s[0:1], 0, v[118:119]
	global_load_dwordx4 v[36:39], v[36:37], off
	v_lshl_add_u64 v[40:41], s[28:29], 0, v[118:119]
	s_add_u32 s0, s7, s26
	global_load_dwordx4 v[40:43], v[40:41], off
	v_lshl_add_u64 v[44:45], s[34:35], 0, v[118:119]
	s_addc_u32 s1, s38, 0
	global_load_dwordx4 v[44:47], v[44:45], off
	v_lshl_add_u64 v[48:49], s[0:1], 0, v[112:113]
	global_load_dwordx4 v[48:51], v[48:49], off
	v_lshl_add_u64 v[56:57], s[0:1], 0, v[120:121]
	global_load_dwordx4 v[56:59], v[56:57], off
	s_waitcnt lgkmcnt(0)
	s_barrier
	s_waitcnt vmcnt(15)
	s_mov_b64 exec, 1
	v_mov_b32_e32 v239, s27
	v_or_b32_e32 v239, 1, v239
	global_store_dword v238, v239, s[98:99] sc0 sc1
	s_mov_b64 exec, -1

.LBB0_514:
	s_and_b64 vcc, exec, s[0:1]
	s_cbranch_vccz .LBB0_520
	s_add_u32 s0, s16, 0xc000
	v_lshlrev_b32_e32 v80, 4, v122
	v_ashrrev_i32_e32 v81, 31, v80
	v_lshl_add_u64 v[0:1], s[8:9], 0, v[80:81]
	v_add_u32_e32 v82, 0x1000, v80
	global_load_dwordx4 v[0:3], v[0:1], off
	v_lshl_add_u64 v[4:5], s[12:13], 0, v[80:81]
	v_ashrrev_i32_e32 v83, 31, v82
	global_load_dwordx4 v[4:7], v[4:5], off
	v_lshl_add_u64 v[8:9], s[8:9], 0, v[82:83]
	v_add_u32_e32 v84, 0x2000, v80
	global_load_dwordx4 v[8:11], v[8:9], off
	v_lshl_add_u64 v[12:13], s[12:13], 0, v[82:83]
	v_ashrrev_i32_e32 v85, 31, v84
	global_load_dwordx4 v[12:15], v[12:13], off
	v_lshl_add_u64 v[16:17], s[8:9], 0, v[84:85]
	v_add_u32_e32 v86, 0x3000, v80
	global_load_dwordx4 v[16:19], v[16:17], off
	v_lshl_add_u64 v[20:21], s[12:13], 0, v[84:85]
	v_ashrrev_i32_e32 v87, 31, v86
	v_add_u32_e32 v40, 0x100, v122
	global_load_dwordx4 v[20:23], v[20:21], off
	v_lshl_add_u64 v[24:25], s[8:9], 0, v[86:87]
	v_lshlrev_b32_e32 v88, 4, v40
	global_load_dwordx4 v[24:27], v[24:25], off
	v_lshl_add_u64 v[28:29], s[12:13], 0, v[86:87]
	s_addc_u32 s1, s17, 0
	v_ashrrev_i32_e32 v89, 31, v88
	global_load_dwordx4 v[28:31], v[28:29], off
	v_lshl_add_u64 v[32:33], s[0:1], 0, v[80:81]
	v_lshl_add_u64 v[36:37], s[0:1], 0, v[88:89]
	v_and_b32_e32 v108, 0xf0, v80
	v_lshrrev_b32_e32 v43, 4, v122
	s_movk_i32 s0, 0x110
	global_load_dwordx4 v[32:35], v[32:33], off
	v_add_u32_e32 v41, 0, v108
	v_mul_lo_u32 v90, v43, s0
	global_load_dwordx4 v[36:39], v[36:37], off
	v_add_u32_e32 v91, v41, v90
	s_waitcnt vmcnt(0)
	ds_write_b128 v91, v[0:3] offset:17408
	v_lshrrev_b32_e32 v0, 3, v122
	s_movk_i32 s1, 0x90
	v_mul_lo_u32 v92, v0, s1
	v_lshrrev_b32_e32 v0, 4, v40
	v_mul_lo_u32 v94, v0, s0
	v_lshrrev_b32_e32 v0, 3, v40
	v_mul_lo_u32 v96, v0, s1
	v_add_u32_e32 v0, 0x200, v122
	v_lshrrev_b32_e32 v1, 4, v0
	v_lshrrev_b32_e32 v0, 3, v0
	v_mul_lo_u32 v100, v0, s1
	v_add_u32_e32 v0, 0x300, v122
	v_mul_lo_u32 v98, v1, s0
	v_lshrrev_b32_e32 v1, 4, v0
	v_lshrrev_b32_e32 v0, 3, v0
	v_and_b32_e32 v111, 0x70, v80
	v_mul_lo_u32 v102, v1, s0
	v_mul_lo_u32 v104, v0, s1
	v_add_u32_e32 v0, 0, v92
	s_add_u32 s0, s16, 0x12000
	v_add_u32_e32 v42, 0, v111
	v_add_u32_e32 v106, v0, v111
	v_add_u32_e32 v0, 0, v96
	s_addc_u32 s1, s17, 0
	v_add_u32_e32 v93, v42, v92
	v_add_u32_e32 v95, v41, v94
	v_add_u32_e32 v97, v42, v96
	v_add_u32_e32 v99, v41, v98
	v_add_u32_e32 v101, v42, v100
	v_add_u32_e32 v103, v41, v102
	v_add_u32_e32 v105, v42, v104
	v_add_u32_e32 v107, v0, v111
	s_add_u32 s8, s16, 0x16000
	ds_write_b128 v93, v[4:7] offset:34816
	ds_write_b128 v95, v[8:11] offset:17408
	ds_write_b128 v97, v[12:15] offset:34816
	ds_write_b128 v99, v[16:19] offset:17408
	ds_write_b128 v101, v[20:23] offset:34816
	ds_write_b128 v103, v[24:27] offset:17408
	ds_write_b128 v105, v[28:31] offset:34816
	ds_write_b128 v106, v[32:35] offset:53248
	ds_write_b128 v107, v[36:39] offset:53248
	s_addc_u32 s9, s17, 0
	v_lshl_add_u64 v[0:1], s[0:1], 0, v[80:81]
	global_load_dwordx4 v[0:3], v[0:1], off
	v_lshl_add_u64 v[4:5], s[8:9], 0, v[80:81]
	global_load_dwordx4 v[4:7], v[4:5], off
	v_lshl_add_u64 v[8:9], s[0:1], 0, v[82:83]
	global_load_dwordx4 v[8:11], v[8:9], off
	v_lshl_add_u64 v[12:13], s[8:9], 0, v[82:83]
	global_load_dwordx4 v[12:15], v[12:13], off
	v_lshl_add_u64 v[16:17], s[0:1], 0, v[84:85]
	global_load_dwordx4 v[16:19], v[16:17], off
	v_lshl_add_u64 v[20:21], s[8:9], 0, v[84:85]
	v_lshl_add_u64 v[24:25], s[0:1], 0, v[86:87]
	s_add_u32 s0, s16, 0x1a000
	global_load_dwordx4 v[20:23], v[20:21], off
	s_addc_u32 s1, s17, 0
	global_load_dwordx4 v[24:27], v[24:25], off
	v_lshl_add_u64 v[28:29], s[8:9], 0, v[86:87]
	v_lshl_add_u64 v[32:33], s[0:1], 0, v[80:81]
	v_lshl_add_u64 v[36:37], s[0:1], 0, v[88:89]
	s_add_u32 s0, s16, 0x20000
	global_load_dwordx4 v[28:31], v[28:29], off
	s_addc_u32 s1, s17, 0
	global_load_dwordx4 v[32:35], v[32:33], off
	s_add_u32 s8, s16, 0x24000
	global_load_dwordx4 v[40:43], v[36:37], off
	s_mov_b64 exec, 1
	v_mov_b32_e32 v239, 0
	global_store_dword v238, v239, s[98:99] sc0 sc1
	s_mov_b64 exec, -1
	s_addc_u32 s9, s17, 0
	v_lshl_add_u64 v[36:37], s[0:1], 0, v[80:81]
	global_load_dwordx4 v[36:39], v[36:37], off
	v_lshl_add_u64 v[44:45], s[8:9], 0, v[80:81]
	global_load_dwordx4 v[44:47], v[44:45], off
	v_lshl_add_u64 v[48:49], s[0:1], 0, v[82:83]
	global_load_dwordx4 v[48:51], v[48:49], off
	v_lshl_add_u64 v[52:53], s[8:9], 0, v[82:83]
	global_load_dwordx4 v[52:55], v[52:53], off
	v_lshl_add_u64 v[56:57], s[0:1], 0, v[84:85]
	global_load_dwordx4 v[56:59], v[56:57], off
	v_lshl_add_u64 v[60:61], s[8:9], 0, v[84:85]
	global_load_dwordx4 v[60:63], v[60:61], off
	v_lshl_add_u64 v[64:65], s[0:1], 0, v[86:87]
	s_add_u32 s0, s16, 0x28000
	global_load_dwordx4 v[64:67], v[64:65], off
	v_lshl_add_u64 v[68:69], s[8:9], 0, v[86:87]
	s_addc_u32 s1, s17, 0
	global_load_dwordx4 v[68:71], v[68:69], off
	v_lshl_add_u64 v[72:73], s[0:1], 0, v[80:81]
	global_load_dwordx4 v[72:75], v[72:73], off
	v_lshl_add_u64 v[76:77], s[0:1], 0, v[88:89]
	s_add_i32 s0, 0, 0x13800
	global_load_dwordx4 v[76:79], v[76:77], off
	v_add_u32_e32 v108, s0, v108
	s_add_i32 s0, 0, 0x17c00
	s_waitcnt lgkmcnt(0)
	s_barrier
	v_add_u32_e32 v109, s0, v111
	s_add_i32 s0, 0, 0x1c400
	v_add_u32_e32 v110, s0, v92
	v_add_u32_e32 v112, s0, v96
	s_mov_b32 s6, 0
	v_add_u32_e32 v110, v110, v111
	v_add_u32_e32 v111, v112, v111
	s_branch .LBB0_517

.LBB0_517:
	v_add_u32_e32 v112, v108, v90
	s_min_u32 s0, s6, 60
	s_waitcnt vmcnt(11)
	s_mov_b64 exec, 1
	v_mov_b32_e32 v239, s6
	global_store_dword v238, v239, s[98:99] sc0 sc1
	s_mov_b64 exec, -1
.Lpf_nopub_b1:
	ds_write_b128 v112, v[0:3]
	v_add_u32_e32 v0, v109, v92
	s_add_i32 s0, s0, 3
	ds_write_b128 v0, v[4:7]
	v_add_u32_e32 v0, v108, v94
	s_mul_i32 s0, s3, s0
	ds_write_b128 v0, v[8:11]
	v_add_u32_e32 v0, v109, v96
	s_add_u32 s7, s16, s0
	ds_write_b128 v0, v[12:15]
	v_add_u32_e32 v0, v108, v98
	s_addc_u32 s12, s17, 0
	ds_write_b128 v0, v[16:19]
	v_add_u32_e32 v0, v109, v100
	s_add_u32 s0, s7, s14
	ds_write_b128 v0, v[20:23]
	v_add_u32_e32 v0, v108, v102
	s_addc_u32 s1, s12, 0
	ds_write_b128 v0, v[24:27]
	v_add_u32_e32 v0, v109, v104
	s_add_u32 s8, s7, s15
	ds_write_b128 v0, v[28:31]
	ds_write_b128 v110, v[32:35]
	ds_write_b128 v111, v[40:43]
	s_addc_u32 s9, s12, 0
	v_lshl_add_u64 v[0:1], s[0:1], 0, v[80:81]
	global_load_dwordx4 v[0:3], v[0:1], off
	v_lshl_add_u64 v[4:5], s[8:9], 0, v[80:81]
	global_load_dwordx4 v[4:7], v[4:5], off
	v_lshl_add_u64 v[8:9], s[0:1], 0, v[82:83]
	global_load_dwordx4 v[8:11], v[8:9], off
	v_lshl_add_u64 v[12:13], s[8:9], 0, v[82:83]
	global_load_dwordx4 v[12:15], v[12:13], off
	v_lshl_add_u64 v[16:17], s[0:1], 0, v[84:85]
	global_load_dwordx4 v[16:19], v[16:17], off
	v_lshl_add_u64 v[20:21], s[8:9], 0, v[84:85]
	global_load_dwordx4 v[20:23], v[20:21], off
	v_lshl_add_u64 v[24:25], s[0:1], 0, v[86:87]
	s_add_u32 s0, s7, s26
	global_load_dwordx4 v[24:27], v[24:25], off
	v_lshl_add_u64 v[28:29], s[8:9], 0, v[86:87]
	s_addc_u32 s1, s12, 0
	global_load_dwordx4 v[28:31], v[28:29], off
	v_lshl_add_u64 v[32:33], s[0:1], 0, v[80:81]
	global_load_dwordx4 v[32:35], v[32:33], off
	v_lshl_add_u64 v[40:41], s[0:1], 0, v[88:89]
	global_load_dwordx4 v[40:43], v[40:41], off
	s_waitcnt lgkmcnt(0)
	s_barrier
	s_waitcnt vmcnt(11)
	s_mov_b64 exec, 1
	v_mov_b32_e32 v239, s6
	v_or_b32_e32 v239, 1, v239
	global_store_dword v238, v239, s[98:99] sc0 sc1
	s_mov_b64 exec, -1

	.amdhsa_kernel _Z14fwd_megakernel4Args
		.amdhsa_group_segment_fixed_size 0
		.amdhsa_private_segment_fixed_size 0
		.amdhsa_kernarg_size 408
		.amdhsa_user_sgpr_count 2
		.amdhsa_user_sgpr_dispatch_ptr 0
		.amdhsa_user_sgpr_queue_ptr 0
		.amdhsa_user_sgpr_kernarg_segment_ptr 1
		.amdhsa_user_sgpr_dispatch_id 0
		.amdhsa_user_sgpr_kernarg_preload_length 0
		.amdhsa_user_sgpr_kernarg_preload_offset 0
		.amdhsa_user_sgpr_private_segment_size 0
		.amdhsa_uses_dynamic_stack 0
		.amdhsa_enable_private_segment 0
		.amdhsa_system_sgpr_workgroup_id_x 1
		.amdhsa_system_sgpr_workgroup_id_y 0
		.amdhsa_system_sgpr_workgroup_id_z 0
		.amdhsa_system_sgpr_workgroup_info 0
		.amdhsa_system_vgpr_workitem_id 2
		.amdhsa_next_free_vgpr 248
		.amdhsa_next_free_sgpr 102
		.amdhsa_accum_offset 248
		.amdhsa_reserve_vcc 1
		.amdhsa_float_round_mode_32 0
		.amdhsa_float_round_mode_16_64 0
		.amdhsa_float_denorm_mode_32 3
		.amdhsa_float_denorm_mode_16_64 3
		.amdhsa_dx10_clamp 1
		.amdhsa_ieee_mode 1
		.amdhsa_fp16_overflow 0
		.amdhsa_tg_split 0
		.amdhsa_exception_fp_ieee_invalid_op 0
		.amdhsa_exception_fp_denorm_src 0
		.amdhsa_exception_fp_ieee_div_zero 0
		.amdhsa_exception_fp_ieee_overflow 0
		.amdhsa_exception_fp_ieee_underflow 0
		.amdhsa_exception_fp_ieee_inexact 0
		.amdhsa_exception_int_div_zero 0
	.end_amdhsa_kernel

amdhsa.kernels:
  - .agpr_count:     0
    .args:
      - .offset:         0
        .size:           152
        .value_kind:     by_value
      - .offset:         152
        .size:           4
        .value_kind:     hidden_block_count_x
      - .offset:         156
        .size:           4
        .value_kind:     hidden_block_count_y
      - .offset:         160
        .size:           4
        .value_kind:     hidden_block_count_z
      - .offset:         164
        .size:           2
        .value_kind:     hidden_group_size_x
      - .offset:         166
        .size:           2
        .value_kind:     hidden_group_size_y
      - .offset:         168
        .size:           2
        .value_kind:     hidden_group_size_z
      - .offset:         170
        .size:           2
        .value_kind:     hidden_remainder_x
      - .offset:         172
        .size:           2
        .value_kind:     hidden_remainder_y
      - .offset:         174
        .size:           2
        .value_kind:     hidden_remainder_z
      - .offset:         192
        .size:           8
        .value_kind:     hidden_global_offset_x
      - .offset:         200
        .size:           8
        .value_kind:     hidden_global_offset_y
      - .offset:         208
        .size:           8
        .value_kind:     hidden_global_offset_z
      - .offset:         216
        .size:           2
        .value_kind:     hidden_grid_dims
      - .offset:         240
        .size:           8
        .value_kind:     hidden_multigrid_sync_arg
      - .offset:         272
        .size:           4
        .value_kind:     hidden_dynamic_lds_size
    .group_segment_fixed_size: 0
    .kernarg_segment_align: 8
    .kernarg_segment_size: 408
    .language:       OpenCL C
    .language_version:
      - 2
      - 0
    .max_flat_workgroup_size: 512
    .name:           _Z14fwd_megakernel4Args
    .private_segment_fixed_size: 0
    .sgpr_count:     108
    .sgpr_spill_count: 4
    .symbol:         _Z14fwd_megakernel4Args.kd
    .uniform_work_group_size: 1
    .uses_dynamic_stack: false
    .vgpr_count:     248
    .vgpr_spill_count: 0
    .wavefront_size: 64
